# P1 gate GEMM: all 24 weight fragments of the wave's K slice fetched up front instead of 4 serialized unroll-2 rounds; LDS A fragments two k-steps ahead; same accumulation order
# speedup vs baseline: 1.0048x; 1.0048x over previous
.LBB0_218:
	s_add_i32 s0, s20, 0xfffff000
	s_lshr_b32 s1, s0, 11
	s_mulk_i32 s1, 0x3000
	s_add_i32 s4, s1, 0x3000
	s_cmpk_lt_i32 s20, 0x1000
	s_cselect_b32 s1, s21, 0
	s_cselect_b32 s0, s20, s0
	s_cselect_b32 s33, s37, s39
	s_cselect_b32 s62, s36, s38
	s_cselect_b32 s4, 0, s4
	s_lshl_b64 s[0:1], s[0:1], 13
	s_add_u32 s0, s62, s0
	s_addc_u32 s1, s33, s1
	s_lshl_b64 s[62:63], s[4:5], 2
	s_add_u32 s62, s10, s62
	s_addc_u32 s63, s11, s63
	s_add_u32 s68, s62, 0x2000
	v_lshl_add_u64 v[24:25], s[0:1], 0, v[110:111]
	s_addc_u32 s69, s63, 0
	global_load_dwordx4 v[44:47], v110, s[0:1]
	global_load_dwordx4 v[52:55], v110, s[0:1] offset:1024
	global_load_dwordx4 v[20:23], v[116:117], off
	global_load_dwordx4 v[16:19], v[116:117], off offset:1024
	global_load_dwordx4 v[162:165], v129, s[68:69]
	global_load_dwordx4 v[170:173], v183, s[68:69]
	global_load_dwordx4 v[4:7], v129, s[62:63]
	global_load_dwordx4 v[0:3], v129, s[62:63] offset:1024
	global_load_dwordx4 v[56:59], v110, s[0:1] offset:2048
	global_load_dwordx4 v[64:67], v110, s[0:1] offset:3072
	global_load_dwordx4 v[36:39], v[116:117], off offset:2048
	global_load_dwordx4 v[32:35], v[116:117], off offset:3072
	global_load_dwordx4 v[174:177], v186, s[68:69]
	global_load_dwordx4 v[198:201], v187, s[68:69]
	global_load_dwordx4 v[12:15], v129, s[62:63] offset:2048
	global_load_dwordx4 v[8:11], v129, s[62:63] offset:3072
	s_movk_i32 s0, 0x1000
	v_add_co_u32_e64 v48, s[0:1], s0, v24
	s_nop 1
	v_addc_co_u32_e64 v49, s[0:1], 0, v25, s[0:1]
	global_load_dwordx4 v[202:205], v188, s[68:69]
	global_load_dwordx4 v[24:27], v188, s[62:63]
	global_load_dwordx4 v[84:87], v[48:49], off
	global_load_dwordx4 v[80:83], v[48:49], off offset:1024
	global_load_dwordx4 v[68:71], v[118:119], off
	global_load_dwordx4 v[60:63], v[120:121], off
	global_load_dwordx4 v[104:107], v189, s[68:69]
	global_load_dwordx4 v[28:31], v189, s[62:63]
	global_load_dwordx4 v[100:103], v190, s[68:69]
	global_load_dwordx4 v[40:43], v190, s[62:63]
	global_load_dwordx4 v[92:95], v[48:49], off offset:2048
	global_load_dwordx4 v[88:91], v[48:49], off offset:3072
	global_load_dwordx4 v[76:79], v[122:123], off
	global_load_dwordx4 v[72:75], v[124:125], off
	global_load_dwordx4 v[96:99], v191, s[68:69]
	s_nop 0
	global_load_dwordx4 v[48:51], v191, s[62:63]
	s_waitcnt vmcnt(31)
	v_mov_b32_e32 v142, v45
	s_waitcnt vmcnt(30)
	v_mov_b32_e32 v143, v53
	v_mov_b32_e32 v146, v47
	v_mov_b32_e32 v147, v55
	v_mov_b32_e32 v138, v44
	v_mov_b32_e32 v139, v52
	v_mov_b32_e32 v140, v46
	v_mov_b32_e32 v141, v54
	s_waitcnt vmcnt(23)
	v_pk_mul_f32 v[148:149], v[58:59], v[58:59]
	v_pk_mul_f32 v[144:145], v[56:57], v[56:57]
	v_pk_mul_f32 v[142:143], v[142:143], v[142:143]
	v_pk_mul_f32 v[146:147], v[146:147], v[146:147]
	v_pk_add_f32 v[152:153], v[162:163], 1.0 op_sel_hi:[1,0]
	v_pk_add_f32 v[162:163], v[172:173], 1.0 op_sel_hi:[1,0]
	s_waitcnt vmcnt(19)
	v_pk_add_f32 v[172:173], v[174:175], 1.0 op_sel_hi:[1,0]
	s_waitcnt vmcnt(18)
	v_pk_add_f32 v[174:175], v[200:201], 1.0 op_sel_hi:[1,0]
	s_waitcnt vmcnt(15)
	v_pk_add_f32 v[200:201], v[202:203], 1.0 op_sel_hi:[1,0]
	v_pk_mov_b32 v[202:203], v[144:145], v[148:149] op_sel:[1,0]
	v_mov_b32_e32 v145, v149
	v_pk_fma_f32 v[138:139], v[138:139], v[138:139], v[142:143]
	v_pk_fma_f32 v[140:141], v[140:141], v[140:141], v[146:147]
	v_mul_f32_e32 v156, v65, v65
	v_mul_f32_e32 v158, v67, v67
	v_pk_add_f32 v[142:143], v[202:203], v[144:145]
	v_pk_add_f32 v[138:139], v[138:139], v[140:141]
	s_waitcnt vmcnt(13)
	v_mul_f32_e32 v133, v84, v84
	v_mul_f32_e32 v210, v85, v85
	v_mul_f32_e32 v211, v86, v86
	v_mul_f32_e32 v212, v87, v87
	v_pk_add_f32 v[150:151], v[164:165], 1.0 op_sel_hi:[1,0]
	v_pk_add_f32 v[164:165], v[170:171], 1.0 op_sel_hi:[1,0]
	v_pk_add_f32 v[170:171], v[176:177], 1.0 op_sel_hi:[1,0]
	v_pk_add_f32 v[176:177], v[198:199], 1.0 op_sel_hi:[1,0]
	v_pk_add_f32 v[198:199], v[204:205], 1.0 op_sel_hi:[1,0]
	v_pk_fma_f32 v[148:149], v[64:65], v[64:65], v[156:157] op_sel_hi:[1,1,0]
	v_pk_fma_f32 v[204:205], v[66:67], v[66:67], v[158:159] op_sel_hi:[1,1,0]
	v_pk_add_f32 v[140:141], v[142:143], v[142:143] op_sel:[0,1] op_sel_hi:[1,0]
	v_pk_add_f32 v[138:139], v[138:139], v[138:139] op_sel:[0,1] op_sel_hi:[1,0]
	s_waitcnt vmcnt(12)
	v_pk_mul_f32 v[160:161], v[82:83], v[82:83]
	v_pk_mul_f32 v[154:155], v[80:81], v[80:81]
	v_mov_b32_e32 v149, v211
	v_mov_b32_e32 v205, v212
	v_mov_b32_e32 v141, v210
	v_mov_b32_e32 v139, v133
	v_pk_mov_b32 v[206:207], v[154:155], v[160:161] op_sel:[1,0]
	v_mov_b32_e32 v155, v161
	v_pk_add_f32 v[142:143], v[148:149], v[204:205]
	v_pk_add_f32 v[138:139], v[138:139], v[140:141]
	s_waitcnt vmcnt(5)
	v_mul_f32_e32 v166, v93, v93
	v_mul_f32_e32 v168, v95, v95
	v_pk_add_f32 v[144:145], v[206:207], v[154:155]
	v_pk_add_f32 v[138:139], v[138:139], v[142:143]
	s_waitcnt vmcnt(4)
	v_mul_f32_e32 v213, v88, v88
	v_mul_f32_e32 v214, v89, v89
	v_mul_f32_e32 v215, v90, v90
	v_mul_f32_e32 v216, v91, v91
	v_pk_fma_f32 v[160:161], v[92:93], v[92:93], v[166:167] op_sel_hi:[1,1,0]
	v_pk_fma_f32 v[208:209], v[94:95], v[94:95], v[168:169] op_sel_hi:[1,1,0]
	v_pk_add_f32 v[144:145], v[144:145], v[144:145] op_sel:[0,1] op_sel_hi:[1,0]
	v_pk_add_f32 v[138:139], v[138:139], v[138:139] op_sel:[0,1] op_sel_hi:[1,0]
	v_mov_b32_e32 v161, v215
	v_mov_b32_e32 v209, v216
	v_mov_b32_e32 v145, v214
	v_mov_b32_e32 v139, v213
	v_pk_add_f32 v[146:147], v[160:161], v[208:209]
	v_pk_add_f32 v[138:139], v[138:139], v[144:145]
	v_lshl_add_u64 v[178:179], s[28:29], 0, v[136:137]
	v_pk_add_f32 v[138:139], v[138:139], v[146:147]
	v_add_co_u32_e64 v178, s[0:1], s16, v178
	v_add_f32_e32 v133, v138, v139
	ds_bpermute_b32 v138, v109, v133
	v_lshl_add_u64 v[180:181], s[28:29], 0, v[134:135]
	v_addc_co_u32_e64 v179, s[0:1], 0, v179, s[0:1]
	v_add_co_u32_e64 v180, s[0:1], s17, v180
	s_waitcnt lgkmcnt(0)
	v_add_f32_e32 v133, v133, v138
	ds_bpermute_b32 v138, v113, v133
	s_mov_b32 s4, 0x800000
	v_addc_co_u32_e64 v181, s[0:1], 0, v181, s[0:1]
	v_mov_b32_e32 v218, v111
	s_waitcnt lgkmcnt(0)
	v_add_f32_e32 v133, v133, v138
	ds_bpermute_b32 v138, v115, v133
	v_mov_b32_e32 v219, v111
	v_pk_add_f32 v[106:107], v[106:107], 1.0 op_sel_hi:[1,0]
	v_pk_add_f32 v[104:105], v[104:105], 1.0 op_sel_hi:[1,0]
	v_pk_add_f32 v[100:101], v[100:101], 1.0 op_sel_hi:[1,0]
	s_waitcnt lgkmcnt(0)
	v_add_f32_e32 v133, v133, v138
	ds_bpermute_b32 v138, v157, v133
	s_waitcnt vmcnt(1)
	v_pk_add_f32 v[96:97], v[96:97], 1.0 op_sel_hi:[1,0]
	v_mov_b32_e32 v220, v111
	v_mov_b32_e32 v221, v111
	v_mov_b32_e32 v222, v111
	s_waitcnt lgkmcnt(0)
	v_add_f32_e32 v133, v133, v138
	ds_bpermute_b32 v138, v159, v133
	v_mov_b32_e32 v223, v111
	v_mov_b32_e32 v224, v111
	v_mov_b32_e32 v225, v111
	v_add_u32_e32 v217, s7, v169
	s_waitcnt lgkmcnt(0)
	v_add_f32_e32 v133, v133, v138
	ds_bpermute_b32 v138, v167, v133
	s_addk_i32 s7, 0x1010
	s_add_u32 s20, s20, 1
	v_pk_add_f32 v[102:103], v[102:103], 1.0 op_sel_hi:[1,0]
	v_pk_add_f32 v[98:99], v[98:99], 1.0 op_sel_hi:[1,0]
	s_waitcnt lgkmcnt(0)
	v_add_f32_e32 v133, v133, v138
	v_fmamk_f32 v133, v133, 0x3a000000, v192
	v_mul_f32_e32 v138, 0x4b800000, v133
	v_cmp_gt_f32_e64 s[0:1], s4, v133
	s_addc_u32 s21, s21, 0
	v_lshl_add_u64 v[134:135], v[134:135], 0, s[8:9]
	v_cndmask_b32_e64 v133, v133, v138, s[0:1]
	v_rsq_f32_e32 v133, v133
	v_lshl_add_u64 v[136:137], v[136:137], 0, s[12:13]
	s_cmpk_eq_i32 s7, 0x4040
	v_mul_f32_e32 v138, 0x45800000, v133
	v_cndmask_b32_e64 v138, v133, v138, s[0:1]
	v_pk_mul_f32 v[44:45], v[44:45], v[138:139] op_sel_hi:[1,0]
	v_pk_mul_f32 v[52:53], v[52:53], v[138:139] op_sel_hi:[1,0]
	v_pk_mul_f32 v[20:21], v[20:21], v[44:45]
	v_pk_mul_f32 v[16:17], v[16:17], v[52:53]
	v_pk_fma_f32 v[4:5], v[152:153], v[20:21], v[4:5]
	v_pk_mul_f32 v[46:47], v[46:47], v[138:139] op_sel_hi:[1,0]
	v_cvt_pk_fp8_f32 v218, v4, v5
	v_pk_mul_f32 v[54:55], v[54:55], v[138:139] op_sel_hi:[1,0]
	v_pk_mul_f32 v[56:57], v[56:57], v[138:139] op_sel_hi:[1,0]
	v_pk_mul_f32 v[64:65], v[64:65], v[138:139] op_sel_hi:[1,0]
	v_pk_mul_f32 v[86:87], v[86:87], v[138:139] op_sel_hi:[1,0]
	v_pk_mul_f32 v[84:85], v[84:85], v[138:139] op_sel_hi:[1,0]
	v_pk_mul_f32 v[82:83], v[82:83], v[138:139] op_sel_hi:[1,0]
	v_pk_mul_f32 v[80:81], v[80:81], v[138:139] op_sel_hi:[1,0]
	v_pk_mul_f32 v[92:93], v[92:93], v[138:139] op_sel_hi:[1,0]
	v_pk_mul_f32 v[88:89], v[88:89], v[138:139] op_sel_hi:[1,0]
	v_pk_fma_f32 v[0:1], v[164:165], v[16:17], v[0:1]
	v_pk_mul_f32 v[22:23], v[22:23], v[46:47]
	v_pk_mul_f32 v[18:19], v[18:19], v[54:55]
	v_pk_mul_f32 v[36:37], v[36:37], v[56:57]
	v_pk_mul_f32 v[32:33], v[32:33], v[64:65]
	v_pk_mul_f32 v[44:45], v[68:69], v[84:85]
	v_pk_mul_f32 v[46:47], v[70:71], v[86:87]
	v_pk_mul_f32 v[52:53], v[60:61], v[80:81]
	v_pk_mul_f32 v[54:55], v[62:63], v[82:83]
	v_pk_mul_f32 v[56:57], v[76:77], v[92:93]
	v_pk_mul_f32 v[60:61], v[72:73], v[88:89]
	v_cvt_pk_fp8_f32 v219, v0, v1
	v_pk_fma_f32 v[6:7], v[150:151], v[22:23], v[6:7]
	v_pk_fma_f32 v[2:3], v[162:163], v[18:19], v[2:3]
	v_pk_fma_f32 v[12:13], v[172:173], v[36:37], v[12:13]
	v_pk_fma_f32 v[8:9], v[176:177], v[32:33], v[8:9]
	v_pk_fma_f32 v[16:17], v[198:199], v[46:47], v[26:27]
	v_pk_fma_f32 v[18:19], v[200:201], v[44:45], v[24:25]
	v_pk_fma_f32 v[20:21], v[106:107], v[54:55], v[30:31]
	v_pk_fma_f32 v[22:23], v[104:105], v[52:53], v[28:29]
	v_pk_fma_f32 v[26:27], v[100:101], v[56:57], v[40:41]
	s_waitcnt vmcnt(0)
	v_pk_fma_f32 v[30:31], v[96:97], v[60:61], v[48:49]
	v_cvt_pk_fp8_f32 v220, v12, v13
	v_cvt_pk_fp8_f32 v221, v8, v9
	v_cvt_pk_fp8_f32 v222, v18, v19
	v_cvt_pk_fp8_f32 v223, v22, v23
	v_cvt_pk_fp8_f32 v224, v26, v27
	v_cvt_pk_fp8_f32 v225, v30, v31
	v_cvt_pk_fp8_f32 v218, v6, v7 op_sel:[0,0,1]
	v_pk_mul_f32 v[58:59], v[58:59], v[138:139] op_sel_hi:[1,0]
	v_pk_mul_f32 v[66:67], v[66:67], v[138:139] op_sel_hi:[1,0]
	v_pk_mul_f32 v[94:95], v[94:95], v[138:139] op_sel_hi:[1,0]
	v_pk_mul_f32 v[90:91], v[90:91], v[138:139] op_sel_hi:[1,0]
	v_pk_mul_f32 v[38:39], v[38:39], v[58:59]
	v_pk_mul_f32 v[34:35], v[34:35], v[66:67]
	v_pk_mul_f32 v[58:59], v[78:79], v[94:95]
	v_pk_mul_f32 v[62:63], v[74:75], v[90:91]
	v_cvt_pk_fp8_f32 v219, v2, v3 op_sel:[0,0,1]
	v_pk_fma_f32 v[14:15], v[170:171], v[38:39], v[14:15]
	v_pk_fma_f32 v[10:11], v[174:175], v[34:35], v[10:11]
	v_pk_fma_f32 v[24:25], v[102:103], v[58:59], v[42:43]
	v_pk_fma_f32 v[28:29], v[98:99], v[62:63], v[50:51]
	v_cvt_pk_bf16_f32 v32, v4, v5
	v_cvt_pk_bf16_f32 v33, v6, v7
	v_cvt_pk_bf16_f32 v4, v0, v1
	v_cvt_pk_bf16_f32 v5, v2, v3
	v_cvt_pk_bf16_f32 v0, v12, v13
	v_cvt_pk_bf16_f32 v1, v14, v15
	v_cvt_pk_bf16_f32 v12, v8, v9
	v_cvt_pk_bf16_f32 v13, v10, v11
	v_cvt_pk_bf16_f32 v8, v18, v19
	v_cvt_pk_bf16_f32 v9, v16, v17
	v_cvt_pk_bf16_f32 v18, v22, v23
	v_cvt_pk_bf16_f32 v19, v20, v21
	v_cvt_pk_bf16_f32 v22, v26, v27
	v_cvt_pk_bf16_f32 v23, v24, v25
	v_cvt_pk_bf16_f32 v26, v30, v31
	v_cvt_pk_bf16_f32 v27, v28, v29
	global_store_dwordx2 v[178:179], v[32:33], off sc1
	ds_write2st64_b64 v217, v[32:33], v[4:5] offset1:1
	ds_write2st64_b64 v217, v[0:1], v[12:13] offset0:2 offset1:3
	ds_write2st64_b64 v217, v[8:9], v[18:19] offset0:4 offset1:5
	ds_write2st64_b64 v217, v[22:23], v[26:27] offset0:6 offset1:7
	v_cvt_pk_fp8_f32 v220, v14, v15 op_sel:[0,0,1]
	v_cvt_pk_fp8_f32 v221, v10, v11 op_sel:[0,0,1]
	v_cvt_pk_fp8_f32 v222, v16, v17 op_sel:[0,0,1]
	v_cvt_pk_fp8_f32 v223, v20, v21 op_sel:[0,0,1]
	v_cvt_pk_fp8_f32 v224, v24, v25 op_sel:[0,0,1]
	v_cvt_pk_fp8_f32 v225, v28, v29 op_sel:[0,0,1]
	global_store_dword v[180:181], v218, off sc1
	global_store_dwordx2 v[178:179], v[4:5], off offset:512 sc1
	global_store_dword v[180:181], v219, off offset:256 sc1
	global_store_dwordx2 v[178:179], v[0:1], off offset:1024 sc1
	global_store_dword v[180:181], v220, off offset:512 sc1
	global_store_dwordx2 v[178:179], v[12:13], off offset:1536 sc1
	global_store_dword v[180:181], v221, off offset:768 sc1
	global_store_dwordx2 v[178:179], v[8:9], off offset:2048 sc1
	global_store_dword v[180:181], v222, off offset:1024 sc1
	global_store_dwordx2 v[178:179], v[18:19], off offset:2560 sc1
	global_store_dword v[180:181], v223, off offset:1280 sc1
	global_store_dwordx2 v[178:179], v[22:23], off offset:3072 sc1
	global_store_dword v[180:181], v224, off offset:1536 sc1
	global_store_dwordx2 v[178:179], v[26:27], off offset:3584 sc1
	global_store_dword v[180:181], v225, off offset:1792 sc1
	s_cbranch_scc0 .LBB0_218
	v_mov_b32_e32 v0, 0
	v_mov_b32_e32 v1, v0
	v_mov_b32_e32 v2, v0
	v_mov_b32_e32 v3, v0
	v_mov_b32_e32 v12, v0
	v_mov_b32_e32 v13, v0
	v_mov_b32_e32 v14, v0
	v_mov_b32_e32 v15, v0
	v_mov_b32_e32 v8, v0
	v_mov_b32_e32 v9, v0
	v_mov_b32_e32 v10, v0
	v_mov_b32_e32 v11, v0
	v_mov_b32_e32 v16, v0
	v_mov_b32_e32 v17, v0
	v_mov_b32_e32 v18, v0
	v_mov_b32_e32 v19, v0
	v_mov_b32_e32 v4, v0
	v_mov_b32_e32 v5, v0
	v_mov_b32_e32 v6, v0
	v_mov_b32_e32 v7, v0
	v_mov_b32_e32 v20, v0
	v_mov_b32_e32 v21, v0
	v_mov_b32_e32 v22, v0
	v_mov_b32_e32 v23, v0
	v_mov_b32_e32 v148, v128
	v_ashrrev_i32_e32 v149, 31, v128
	s_mov_b32 s98, 0x10000
	s_mov_b32 s99, 0
	s_mov_b32 s100, 0x20000
	s_mov_b32 s101, 0
	v_lshl_add_u64 v[148:149], v[148:149], 1, v[126:127]
	v_add_u32_e32 v150, 0x10100, v182
	v_lshl_add_u64 v[164:165], v[148:149], 0, s[98:99]
	v_lshl_add_u64 v[170:171], v[148:149], 0, s[100:101]
	global_load_dwordx4 v[28:31], v[148:149], off
	global_load_dwordx4 v[32:35], v[164:165], off
	global_load_dwordx4 v[36:39], v[170:171], off
	global_load_dwordx4 v[40:43], v[148:149], off offset:64
	global_load_dwordx4 v[44:47], v[164:165], off offset:64
	global_load_dwordx4 v[48:51], v[170:171], off offset:64
	global_load_dwordx4 v[136:139], v[148:149], off offset:128
	global_load_dwordx4 v[140:143], v[164:165], off offset:128
	global_load_dwordx4 v[144:147], v[170:171], off offset:128
	global_load_dwordx4 v[160:163], v[148:149], off offset:192
	global_load_dwordx4 v[198:201], v[164:165], off offset:192
	global_load_dwordx4 v[202:205], v[170:171], off offset:192
	global_load_dwordx4 v[206:209], v[148:149], off offset:256
	global_load_dwordx4 v[210:213], v[164:165], off offset:256
	global_load_dwordx4 v[214:217], v[170:171], off offset:256
	global_load_dwordx4 v[218:221], v[148:149], off offset:320
	global_load_dwordx4 v[222:225], v[164:165], off offset:320
	global_load_dwordx4 v[226:229], v[170:171], off offset:320
	global_load_dwordx4 v[230:233], v[148:149], off offset:384
	global_load_dwordx4 v[234:237], v[164:165], off offset:384
	global_load_dwordx4 v[238:241], v[170:171], off offset:384
	s_waitcnt lgkmcnt(0)
	s_barrier
	ds_read_b128 v[24:27], v182
	ds_read_b128 v[152:155], v150
	ds_read_b128 v[178:181], v182 offset:64
	ds_read_b128 v[246:249], v150 offset:64
	s_waitcnt vmcnt(18) lgkmcnt(2)
	v_mfma_f32_16x16x32_bf16 v[0:3], v[24:27], v[28:31], v[0:3]
	v_mfma_f32_16x16x32_bf16 v[16:19], v[152:155], v[28:31], v[16:19]
	v_mfma_f32_16x16x32_bf16 v[12:15], v[24:27], v[32:35], v[12:15]
	v_mfma_f32_16x16x32_bf16 v[4:7], v[152:155], v[32:35], v[4:7]
	v_mfma_f32_16x16x32_bf16 v[8:11], v[24:27], v[36:39], v[8:11]
	v_mfma_f32_16x16x32_bf16 v[20:23], v[152:155], v[36:39], v[20:23]
	global_load_dwordx4 v[28:31], v[148:149], off offset:448
	global_load_dwordx4 v[32:35], v[164:165], off offset:448
	global_load_dwordx4 v[36:39], v[170:171], off offset:448
	ds_read_b128 v[24:27], v182 offset:128
	ds_read_b128 v[152:155], v150 offset:128
	s_waitcnt vmcnt(18) lgkmcnt(2)
	v_mfma_f32_16x16x32_bf16 v[0:3], v[178:181], v[40:43], v[0:3]
	v_mfma_f32_16x16x32_bf16 v[16:19], v[246:249], v[40:43], v[16:19]
	v_mfma_f32_16x16x32_bf16 v[12:15], v[178:181], v[44:47], v[12:15]
	v_mfma_f32_16x16x32_bf16 v[4:7], v[246:249], v[44:47], v[4:7]
	v_mfma_f32_16x16x32_bf16 v[8:11], v[178:181], v[48:51], v[8:11]
	v_mfma_f32_16x16x32_bf16 v[20:23], v[246:249], v[48:51], v[20:23]
	ds_read_b128 v[178:181], v182 offset:192
	ds_read_b128 v[246:249], v150 offset:192
	s_waitcnt vmcnt(15) lgkmcnt(2)
	v_mfma_f32_16x16x32_bf16 v[0:3], v[24:27], v[136:139], v[0:3]
	v_mfma_f32_16x16x32_bf16 v[16:19], v[152:155], v[136:139], v[16:19]
	v_mfma_f32_16x16x32_bf16 v[12:15], v[24:27], v[140:143], v[12:15]
	v_mfma_f32_16x16x32_bf16 v[4:7], v[152:155], v[140:143], v[4:7]
	v_mfma_f32_16x16x32_bf16 v[8:11], v[24:27], v[144:147], v[8:11]
	v_mfma_f32_16x16x32_bf16 v[20:23], v[152:155], v[144:147], v[20:23]
	ds_read_b128 v[24:27], v182 offset:256
	ds_read_b128 v[152:155], v150 offset:256
	s_waitcnt vmcnt(12) lgkmcnt(2)
	v_mfma_f32_16x16x32_bf16 v[0:3], v[178:181], v[160:163], v[0:3]
	v_mfma_f32_16x16x32_bf16 v[16:19], v[246:249], v[160:163], v[16:19]
	v_mfma_f32_16x16x32_bf16 v[12:15], v[178:181], v[198:201], v[12:15]
	v_mfma_f32_16x16x32_bf16 v[4:7], v[246:249], v[198:201], v[4:7]
	v_mfma_f32_16x16x32_bf16 v[8:11], v[178:181], v[202:205], v[8:11]
	v_mfma_f32_16x16x32_bf16 v[20:23], v[246:249], v[202:205], v[20:23]
	ds_read_b128 v[178:181], v182 offset:320
	ds_read_b128 v[246:249], v150 offset:320
	s_waitcnt vmcnt(9) lgkmcnt(2)
	v_mfma_f32_16x16x32_bf16 v[0:3], v[24:27], v[206:209], v[0:3]
	v_mfma_f32_16x16x32_bf16 v[16:19], v[152:155], v[206:209], v[16:19]
	v_mfma_f32_16x16x32_bf16 v[12:15], v[24:27], v[210:213], v[12:15]
	v_mfma_f32_16x16x32_bf16 v[4:7], v[152:155], v[210:213], v[4:7]
	v_mfma_f32_16x16x32_bf16 v[8:11], v[24:27], v[214:217], v[8:11]
	v_mfma_f32_16x16x32_bf16 v[20:23], v[152:155], v[214:217], v[20:23]
	ds_read_b128 v[24:27], v182 offset:384
	ds_read_b128 v[152:155], v150 offset:384
	s_waitcnt vmcnt(6) lgkmcnt(2)
	v_mfma_f32_16x16x32_bf16 v[0:3], v[178:181], v[218:221], v[0:3]
	v_mfma_f32_16x16x32_bf16 v[16:19], v[246:249], v[218:221], v[16:19]
	v_mfma_f32_16x16x32_bf16 v[12:15], v[178:181], v[222:225], v[12:15]
	v_mfma_f32_16x16x32_bf16 v[4:7], v[246:249], v[222:225], v[4:7]
	v_mfma_f32_16x16x32_bf16 v[8:11], v[178:181], v[226:229], v[8:11]
	v_mfma_f32_16x16x32_bf16 v[20:23], v[246:249], v[226:229], v[20:23]
	ds_read_b128 v[178:181], v182 offset:448
	ds_read_b128 v[246:249], v150 offset:448
	s_waitcnt vmcnt(3) lgkmcnt(2)
	v_mfma_f32_16x16x32_bf16 v[0:3], v[24:27], v[230:233], v[0:3]
	v_mfma_f32_16x16x32_bf16 v[16:19], v[152:155], v[230:233], v[16:19]
	v_mfma_f32_16x16x32_bf16 v[12:15], v[24:27], v[234:237], v[12:15]
	v_mfma_f32_16x16x32_bf16 v[4:7], v[152:155], v[234:237], v[4:7]
	v_mfma_f32_16x16x32_bf16 v[8:11], v[24:27], v[238:241], v[8:11]
	v_mfma_f32_16x16x32_bf16 v[20:23], v[152:155], v[238:241], v[20:23]
	s_waitcnt vmcnt(0) lgkmcnt(0)
	v_mfma_f32_16x16x32_bf16 v[0:3], v[178:181], v[28:31], v[0:3]
	v_mfma_f32_16x16x32_bf16 v[16:19], v[246:249], v[28:31], v[16:19]
	v_mfma_f32_16x16x32_bf16 v[12:15], v[178:181], v[32:35], v[12:15]
	v_mfma_f32_16x16x32_bf16 v[4:7], v[246:249], v[32:35], v[4:7]
	v_mfma_f32_16x16x32_bf16 v[8:11], v[178:181], v[36:39], v[8:11]
	v_mfma_f32_16x16x32_bf16 v[20:23], v[246:249], v[36:39], v[20:23]
	s_barrier
	ds_write_b32 v193, v0
	ds_write_b32 v193, v1 offset:192
	ds_write_b32 v193, v2 offset:384
	ds_write_b32 v194, v3
	ds_write_b32 v193, v12 offset:64
	ds_write_b32 v193, v13 offset:256
	ds_write_b32 v193, v14 offset:448
	ds_write_b32 v194, v15 offset:64
	ds_write_b32 v193, v8 offset:128
	ds_write_b32 v193, v9 offset:320
	ds_write_b32 v193, v10 offset:512
	ds_write_b32 v194, v11 offset:128
	ds_write_b32 v193, v16 offset:3072
	ds_write_b32 v193, v17 offset:3264
	ds_write_b32 v193, v18 offset:3456
	ds_write_b32 v195, v19
	ds_write_b32 v193, v4 offset:3136
	ds_write_b32 v193, v5 offset:3328
	ds_write_b32 v193, v6 offset:3520
	ds_write_b32 v195, v7 offset:64
	ds_write_b32 v193, v20 offset:3200
	ds_write_b32 v193, v21 offset:3392
	ds_write_b32 v193, v22 offset:3584
	ds_write_b32 v195, v23 offset:128
	s_waitcnt lgkmcnt(0)
	s_barrier
	s_and_saveexec_b64 s[20:21], vcc
	s_cbranch_execz .LBB0_216
	s_lshl_b32 s4, s85, 5
	v_lshl_add_u32 v1, v108, 2, 0
	s_mov_b64 s[62:63], 0
	v_mov_b32_e32 v0, v108
	s_branch .LBB0_224
